# lever 4: one static s_setprio 1 for waves 4-7 at kernel start, every other s_setprio removed (v12 base)
# baseline (speedup 1.0000x reference)
; #define GAS __attribute__((address_space(1)))
; #define LAS __attribute__((address_space(3)))
; __device__ __forceinline__ unsigned xb_add(unsigned* p, unsigned v) { return __hip_atomic_fetch_add(p, v, __ATOMIC_RELAXED, __HIP_MEMORY_SCOPE_AGENT); }
; __device__ __forceinline__ unsigned xb_xcc_id() { return (unsigned)__builtin_amdgcn_s_getreg((3 << 11) | 20) & 0xFu; }
; __device__ __forceinline__ ArgsP getargs() { ArgsP p = (ArgsP)__builtin_amdgcn_kernarg_segment_ptr(); asm volatile("" : "+s"(p)); return p; }
; __global__ void __launch_bounds__(512, 2) mega(Args a_unused) {
;     extern __shared__ __attribute__((aligned(16))) unsigned char lds[];
;     cg::grid_group grid = cg::this_grid();
;     int ph = 0;
;     if (threadIdx.x < 2) ((volatile LAS unsigned*)((LAS unsigned char*)lds + (LDS_BYTES - 64)))[threadIdx.x] = 0u;
;     __syncthreads();
;     { ArgsP a0 = getargs(); unsigned char* ws = (unsigned char*)(GAS unsigned char*)a0->ws; if (threadIdx.x == 0) (void)xb_add(&((unsigned*)(ws + 16384))[XB_XCNT(xb_xcc_id())], 1u); }
_Z4mega4Args:
	s_mov_b64 s[84:85], s[0:1]
	s_load_dwordx2 s[92:93], s[0:1], 0x128
	s_load_dword s50, s[0:1], 0x130
	s_add_u32 s0, s84, 0x128
	s_addc_u32 s1, s85, 0
	v_and_b32_e32 v180, 0x3ff, v0
	v_readfirstlane_b32 s32, v180
	s_nop 3
	s_lshr_b32 s32, s32, 6
	s_cmp_ge_u32 s32, 4
	s_cbranch_scc0 .Lprio_done
	s_setprio 1
.Lprio_done:
	v_writelane_b32 v255, s0, 0
	s_mov_b32 s73, s2
	v_cmp_gt_u32_e32 vcc, 2, v180
	v_writelane_b32 v255, s1, 1
	s_and_saveexec_b64 s[4:5], vcc
	v_lshl_add_u32 v1, v180, 2, 0
	v_add_u32_e32 v1, 0x257c0, v1
	v_mov_b32_e32 v2, 0
	ds_write_b32 v1, v2
	s_or_b64 exec, exec, s[4:5]
	s_mov_b64 s[6:7], s[84:85]
	v_cmp_eq_u32_e64 s[82:83], 0, v180
	s_waitcnt lgkmcnt(0)
	s_barrier
	s_and_saveexec_b64 s[4:5], s[82:83]
	s_cbranch_execz .LBB0_5
	s_mov_b64 s[8:9], exec
	v_mbcnt_lo_u32_b32 v1, s8, 0
	v_mbcnt_hi_u32_b32 v1, s9, v1
	v_cmp_eq_u32_e32 vcc, 0, v1
	s_getreg_b32 s0, hwreg(HW_REG_XCC_ID, 0, 4)
	s_and_b64 s[2:3], exec, vcc
	s_mov_b64 exec, s[2:3]
	s_cbranch_execz .LBB0_5
	s_load_dwordx2 s[2:3], s[6:7], 0x118
	s_lshl_b32 s0, s0, 8
	s_and_b32 s0, s0, 0xf00
	v_mov_b32_e32 v1, 0x4000
	s_waitcnt lgkmcnt(0)
	s_add_u32 s0, s2, s0
	s_addc_u32 s1, s3, 0
	s_bcnt1_i32_b64 s2, s[8:9]
	v_mov_b32_e32 v2, s2
	global_atomic_add v1, v2, s[0:1] offset:1024

; __device__ __forceinline__ unsigned f2bf(float f) { unsigned u = __builtin_bit_cast(unsigned, f); return (u + 0x7fffu + ((u >> 16) & 1u)) >> 16; }
; __device__ __forceinline__ int crow(int r, int hi) { return (r & 3) + 8 * (r >> 2) + 4 * hi; }
; __device__ __forceinline__ void attn_item(const bf16_t* __restrict__ Qb, const bf16_t* __restrict__ Kn, const bf16_t* __restrict__ Kr, const bf16_t* __restrict__ Vh,
;                                           const float* __restrict__ csq, bf16_t* __restrict__ Ob, int seq, char* lds) {
;     ...
;   __builtin_amdgcn_s_setprio(0);
;   if (hi == 0) li_l[r32] = l_reg; asm volatile("s_waitcnt lgkmcnt(0)" ::: "memory");
;   float rli[16];
; #pragma unroll
;   for (int r = 0; r < 16; ++r) rli[r] = __builtin_amdgcn_rcpf(li_l[crow(r, hi)]);
;   bf16_t* Ow = Ob + (long)(wid * QBLK) * DM;
; #pragma unroll
;   for (int r = 0; r < 16; ++r) { int orow = crow(r, hi);
; #pragma unroll
;     for (int d0 = 0; d0 < 2; ++d0) Ow[(long)orow * DM + d0 * 32 + r32] = (bf16_t)f2bf(o[d0][r] * rli[r]); }
.Lat_rr_31:
	s_barrier
	s_nop 7
	s_nop 7
	v_mov_b32_e32 v177, v174
	s_nop 1
	v_permlane32_swap_b32_e32 v174, v177
	v_add_f32_e32 v174, v174, v177
	s_mov_b32 exec_hi, 0
	ds_write_b32 v175, v174
	s_mov_b64 exec, -1
	s_waitcnt lgkmcnt(0)
	ds_read_b128 v[184:187], v176 offset:0
	ds_read_b128 v[188:191], v176 offset:32
	ds_read_b128 v[192:195], v176 offset:64
	ds_read_b128 v[196:199], v176 offset:96
	v_and_b32_e32 v1, 63, v180
	v_and_b32_e32 v178, 31, v1
	v_lshrrev_b32_e32 v179, 5, v1
	s_lshl_b32 s30, s29, 16
	v_lshlrev_b32_e32 v177, 13, v179
	v_add_u32_e32 v177, s30, v177
	v_lshl_add_u32 v177, v178, 1, v177
	s_waitcnt lgkmcnt(0)
	v_rcp_f32_e32 v184, v184
	v_rcp_f32_e32 v185, v185
	v_rcp_f32_e32 v186, v186
	v_rcp_f32_e32 v187, v187
	v_rcp_f32_e32 v188, v188
	v_rcp_f32_e32 v189, v189
	v_rcp_f32_e32 v190, v190
	v_rcp_f32_e32 v191, v191
	v_rcp_f32_e32 v192, v192
	v_rcp_f32_e32 v193, v193
	v_rcp_f32_e32 v194, v194
	v_rcp_f32_e32 v195, v195
	v_rcp_f32_e32 v196, v196
	v_rcp_f32_e32 v197, v197
	v_rcp_f32_e32 v198, v198
	v_rcp_f32_e32 v199, v199
	s_nop 0
	v_add_u32_e32 v200, 0, v177
	v_add_u32_e32 v201, 4096, v177
	v_add_u32_e32 v202, 16384, v177
	v_add_u32_e32 v203, 20480, v177
	v_add_u32_e32 v204, 32768, v177
	v_add_u32_e32 v205, 36864, v177
	v_add_u32_e32 v206, 49152, v177
	v_add_u32_e32 v207, 53248, v177
	v_mul_f32_e32 v2, v2, v184
	v_bfe_u32 v1, v2, 16, 1
	v_add3_u32 v2, v2, v1, s25
	global_store_short_d16_hi v200, v2, s[26:27] offset:0
	v_mul_f32_e32 v18, v18, v184
	v_bfe_u32 v1, v18, 16, 1
	v_add3_u32 v18, v18, v1, s25
	global_store_short_d16_hi v200, v18, s[26:27] offset:64
	v_mul_f32_e32 v3, v3, v185
	v_bfe_u32 v1, v3, 16, 1
	v_add3_u32 v3, v3, v1, s25
	global_store_short_d16_hi v200, v3, s[26:27] offset:2048
	v_mul_f32_e32 v19, v19, v185
	v_bfe_u32 v1, v19, 16, 1
	v_add3_u32 v19, v19, v1, s25
	global_store_short_d16_hi v200, v19, s[26:27] offset:2112
	v_mul_f32_e32 v4, v4, v186
	v_bfe_u32 v1, v4, 16, 1
	v_add3_u32 v4, v4, v1, s25
	global_store_short_d16_hi v201, v4, s[26:27] offset:0
	v_mul_f32_e32 v20, v20, v186
	v_bfe_u32 v1, v20, 16, 1
	v_add3_u32 v20, v20, v1, s25
	global_store_short_d16_hi v201, v20, s[26:27] offset:64
	v_mul_f32_e32 v5, v5, v187
	v_bfe_u32 v1, v5, 16, 1
	v_add3_u32 v5, v5, v1, s25
	global_store_short_d16_hi v201, v5, s[26:27] offset:2048
	v_mul_f32_e32 v21, v21, v187
	v_bfe_u32 v1, v21, 16, 1
	v_add3_u32 v21, v21, v1, s25
	global_store_short_d16_hi v201, v21, s[26:27] offset:2112
	v_mul_f32_e32 v6, v6, v188
	v_bfe_u32 v1, v6, 16, 1
	v_add3_u32 v6, v6, v1, s25
	global_store_short_d16_hi v202, v6, s[26:27] offset:0
	v_mul_f32_e32 v22, v22, v188
	v_bfe_u32 v1, v22, 16, 1
	v_add3_u32 v22, v22, v1, s25
	global_store_short_d16_hi v202, v22, s[26:27] offset:64
	v_mul_f32_e32 v7, v7, v189
	v_bfe_u32 v1, v7, 16, 1
	v_add3_u32 v7, v7, v1, s25
	global_store_short_d16_hi v202, v7, s[26:27] offset:2048
	v_mul_f32_e32 v23, v23, v189
	v_bfe_u32 v1, v23, 16, 1
	v_add3_u32 v23, v23, v1, s25
	global_store_short_d16_hi v202, v23, s[26:27] offset:2112
	v_mul_f32_e32 v8, v8, v190
	v_bfe_u32 v1, v8, 16, 1
	v_add3_u32 v8, v8, v1, s25
	global_store_short_d16_hi v203, v8, s[26:27] offset:0
	v_mul_f32_e32 v24, v24, v190
	v_bfe_u32 v1, v24, 16, 1
	v_add3_u32 v24, v24, v1, s25
	global_store_short_d16_hi v203, v24, s[26:27] offset:64
	v_mul_f32_e32 v9, v9, v191
	v_bfe_u32 v1, v9, 16, 1
	v_add3_u32 v9, v9, v1, s25
	global_store_short_d16_hi v203, v9, s[26:27] offset:2048
	v_mul_f32_e32 v25, v25, v191
	v_bfe_u32 v1, v25, 16, 1
	v_add3_u32 v25, v25, v1, s25
	global_store_short_d16_hi v203, v25, s[26:27] offset:2112
	v_mul_f32_e32 v10, v10, v192
	v_bfe_u32 v1, v10, 16, 1
	v_add3_u32 v10, v10, v1, s25
	global_store_short_d16_hi v204, v10, s[26:27] offset:0
	v_mul_f32_e32 v26, v26, v192
	v_bfe_u32 v1, v26, 16, 1
	v_add3_u32 v26, v26, v1, s25
	global_store_short_d16_hi v204, v26, s[26:27] offset:64
	v_mul_f32_e32 v11, v11, v193
	v_bfe_u32 v1, v11, 16, 1
	v_add3_u32 v11, v11, v1, s25
	global_store_short_d16_hi v204, v11, s[26:27] offset:2048
	v_mul_f32_e32 v27, v27, v193
	v_bfe_u32 v1, v27, 16, 1
	v_add3_u32 v27, v27, v1, s25
	global_store_short_d16_hi v204, v27, s[26:27] offset:2112
	v_mul_f32_e32 v12, v12, v194
	v_bfe_u32 v1, v12, 16, 1
	v_add3_u32 v12, v12, v1, s25
	global_store_short_d16_hi v205, v12, s[26:27] offset:0
	v_mul_f32_e32 v28, v28, v194
	v_bfe_u32 v1, v28, 16, 1
	v_add3_u32 v28, v28, v1, s25
	global_store_short_d16_hi v205, v28, s[26:27] offset:64
	v_mul_f32_e32 v13, v13, v195
	v_bfe_u32 v1, v13, 16, 1
	v_add3_u32 v13, v13, v1, s25
	global_store_short_d16_hi v205, v13, s[26:27] offset:2048
	v_mul_f32_e32 v29, v29, v195
	v_bfe_u32 v1, v29, 16, 1
	v_add3_u32 v29, v29, v1, s25
	global_store_short_d16_hi v205, v29, s[26:27] offset:2112
	v_mul_f32_e32 v14, v14, v196
	v_bfe_u32 v1, v14, 16, 1
	v_add3_u32 v14, v14, v1, s25
	global_store_short_d16_hi v206, v14, s[26:27] offset:0
	v_mul_f32_e32 v30, v30, v196
	v_bfe_u32 v1, v30, 16, 1
	v_add3_u32 v30, v30, v1, s25
	global_store_short_d16_hi v206, v30, s[26:27] offset:64
	v_mul_f32_e32 v15, v15, v197
	v_bfe_u32 v1, v15, 16, 1
	v_add3_u32 v15, v15, v1, s25
	global_store_short_d16_hi v206, v15, s[26:27] offset:2048
	v_mul_f32_e32 v31, v31, v197
	v_bfe_u32 v1, v31, 16, 1
	v_add3_u32 v31, v31, v1, s25
	global_store_short_d16_hi v206, v31, s[26:27] offset:2112
	v_mul_f32_e32 v16, v16, v198
	v_bfe_u32 v1, v16, 16, 1
	v_add3_u32 v16, v16, v1, s25
	global_store_short_d16_hi v207, v16, s[26:27] offset:0
	v_mul_f32_e32 v32, v32, v198
	v_bfe_u32 v1, v32, 16, 1
	v_add3_u32 v32, v32, v1, s25
	global_store_short_d16_hi v207, v32, s[26:27] offset:64
	v_mul_f32_e32 v17, v17, v199
	v_bfe_u32 v1, v17, 16, 1
	v_add3_u32 v17, v17, v1, s25
	global_store_short_d16_hi v207, v17, s[26:27] offset:2048
	v_mul_f32_e32 v33, v33, v199
	v_bfe_u32 v1, v33, 16, 1
	v_add3_u32 v33, v33, v1, s25
	global_store_short_d16_hi v207, v33, s[26:27] offset:2112
	s_add_i32 s28, s28, s92
	s_cmpk_lt_i32 s28, 0x400
	s_cbranch_scc1 .Lat_item
	s_branch .Lat_done
